# speedup vs baseline: 1.0076x; 1.0076x over previous
; #define LAS __attribute__((address_space(3)))
; __device__ __forceinline__ void attn_phase(LAS unsigned char* lds, bf16_t* Qb, const bf16_t* KVb, const bf16_t* GZ, const float* sinkp) {
;     ...
;         if (!mu) { head = kvh * 4 + hp2 + (w & 1); const int i = rb * 128 + 32 * (w >> 1) + q; qrow = sbase + i; uq = 16 + i; st = true; }
;         else { head = kvh * 4 + (w & 3); qrow = NREAL + seq * 16 + (q & 15); uq = q & 15; st = (w < 4) && (q < 16); }
;         const int b0 = mu ? 0 : (rb > 0 ? rb - 1 : 0), b1 = mu ? 0 : (rb + 1 < NB ? rb + 1 : NB - 1);
;         const int ntiles = 1 + 2 * (b1 - b0 + 1);
;         LAS unsigned char* Wl = lds + 65536 + w * 8192;
;         const int row0 = sbase + rb * 128 + 32 * (w >> 1), crr = lane >> 4, cch = lane & 15;
;         bf16x8 qf[8];
;         {
;             int qi = q, hi = h, cri = crr, chi = cch; asm volatile("" : "+v"(qi), "+v"(hi), "+v"(cri), "+v"(chi));
; #pragma unroll 4
;             for (int it = 0; it < 8; ++it) {
;                 const int rr = cri + 4 * it, grow = mu ? NREAL + seq * 16 + (rr & 15) : row0 + rr;
;                 const u32x4 v = *(const u32x4*)(Qb + (size_t)grow * 2048 + head * 128 + chi * 8);
;                 *(LAS u32x4*)(Wl + rr * 256 + ((chi ^ (rr & 15)) << 4)) = v;
;             }
; #pragma unroll
;             for (int ks = 0; ks < 8; ++ks) qf[ks] = *(const LAS bf16x8*)(Wl + qi * 256 + (((2 * ks + hi) ^ (qi & 15)) << 4));
;         }
;         float m_run = sinkp[head] * 1.4426950408889634f, l_run = 1.f;
;         f32x16 o[4];
; #pragma unroll
;         for (int dt = 0; dt < 4; ++dt)
; #pragma unroll
;             for (int r = 0; r < 16; ++r) o[dt][r] = 0.f;
;         u32x4 kreg[2], vreg[2];
;         {
;             u32x4 k0r[2], v0r[2], k1r[2], v1r[2];
;             const bf16_t* kp0 = KVb + (size_t)(NREAL + seq * 16 + srow) * 1024 + kvh * 128 + sch * 8;
;             const bf16_t* kp1 = KVb + (size_t)(sbase + b0 * 128 + srow) * 1024 + kvh * 128 + sch * 8;
;             k0r[0] = *(const u32x4*)kp0; k0r[1] = *(const u32x4*)(kp0 + 32 * 1024); v0r[0] = *(const u32x4*)(kp0 + 512); v0r[1] = *(const u32x4*)(kp0 + 512 + 32 * 1024);
;             k1r[0] = *(const u32x4*)kp1; k1r[1] = *(const u32x4*)(kp1 + 32 * 1024); v1r[0] = *(const u32x4*)(kp1 + 512); v1r[1] = *(const u32x4*)(kp1 + 512 + 32 * 1024);
.LBB0_162:
	s_lshl_b32 s36, s70, 11
	s_addk_i32 s36, 0x1800
	s_cmp_lg_u32 s70, 0
	s_cselect_b32 s71, s36, 0
	v_mov_b32_e32 v3, v149
	v_mov_b32_e32 v8, v159
	v_mov_b32_e32 v2, v148
	v_mov_b32_e32 v9, v158
	s_lshl_b32 s98, s58, 7
	s_lshl_b32 s36, s58, 8
	s_add_u32 s36, s16, s36
	v_add_u32_e32 v7, 4, v9
	s_addc_u32 s37, s17, 0
	v_lshlrev_b32_e32 v0, 3, v8
	s_lshl_b32 s60, s70, 4
	v_and_b32_e32 v5, 15, v7
	s_waitcnt vmcnt(3)
	v_bitop3_b32 v10, v9, 8, 15 bitop3:0x6c
	v_add_u32_e32 v11, 12, v9
	v_bitop3_b32 v7, v7, v8, 15 bitop3:0x6c
	v_ashrrev_i32_e32 v1, 31, v0
	s_addk_i32 s60, 0x6000
	s_waitcnt vmcnt(2)
	v_and_b32_e32 v12, 15, v11
	v_bitop3_b32 v13, v9, v8, 15 bitop3:0x6c
	s_waitcnt vmcnt(2)
	v_lshlrev_b32_e32 v14, 4, v7
	v_xor_b32_e32 v7, v10, v8
	v_bitop3_b32 v8, v11, v8, 15 bitop3:0x6c
	s_add_i32 s61, s73, s71
	v_lshl_add_u64 v[0:1], v[0:1], 1, s[36:37]
	v_and_b32_e32 v6, 15, v9
	v_lshlrev_b32_e32 v13, 4, v13
	v_lshlrev_b32_e32 v10, 4, v7
	v_or_b32_e32 v7, s60, v12
	v_lshlrev_b32_e32 v8, 4, v8
	v_lshlrev_b32_e32 v12, 8, v9
	s_add_i32 s36, s61, s66
	s_mov_b32 s59, 0
	v_or_b32_e32 v4, s60, v6
	v_or_b32_e32 v5, s60, v5
	v_bitop3_b32 v6, v6, s60, 8 bitop3:0xde
	v_add3_u32 v8, v12, v8, s65
	v_add_u32_e32 v9, s36, v9
	v_add3_u32 v10, v12, v10, s67
	v_add3_u32 v11, v12, v14, s68
	v_add3_u32 v12, v12, v13, s63
	v_mov_b32_e32 v60, v12
	v_mov_b32_e32 v61, v11
	v_mov_b32_e32 v62, v10
	v_mov_b32_e32 v63, v8
	v_add_u32_e32 v114, -12, v9
	v_cndmask_b32_e64 v112, v114, v4, s[4:5]
	v_ashrrev_i32_e32 v113, 31, v112
	v_lshlrev_b64 v[112:113], 12, v[112:113]
	v_lshl_add_u64 v[112:113], v[0:1], 0, v[112:113]
	global_load_dwordx4 v[112:115], v[112:113], off nt
	v_add_u32_e32 v118, -8, v9
	v_cndmask_b32_e64 v116, v118, v5, s[4:5]
	v_ashrrev_i32_e32 v117, 31, v116
	v_lshlrev_b64 v[116:117], 12, v[116:117]
	v_lshl_add_u64 v[116:117], v[0:1], 0, v[116:117]
	global_load_dwordx4 v[116:119], v[116:117], off nt
	v_add_u32_e32 v122, -4, v9
	v_cndmask_b32_e64 v120, v122, v6, s[4:5]
	v_ashrrev_i32_e32 v121, 31, v120
	v_lshlrev_b64 v[120:121], 12, v[120:121]
	v_lshl_add_u64 v[120:121], v[0:1], 0, v[120:121]
	global_load_dwordx4 v[120:123], v[120:121], off nt
	v_add_u32_e32 v126, 0, v9
	v_cndmask_b32_e64 v124, v126, v7, s[4:5]
	v_ashrrev_i32_e32 v125, 31, v124
	v_lshlrev_b64 v[124:125], 12, v[124:125]
	v_lshl_add_u64 v[124:125], v[0:1], 0, v[124:125]
	global_load_dwordx4 v[124:127], v[124:125], off nt
	v_add_u32_e32 v130, 4, v9
	v_cndmask_b32_e64 v128, v130, v4, s[4:5]
	v_ashrrev_i32_e32 v129, 31, v128
	v_lshlrev_b64 v[128:129], 12, v[128:129]
	v_lshl_add_u64 v[128:129], v[0:1], 0, v[128:129]
	global_load_dwordx4 v[128:131], v[128:129], off nt
	v_add_u32_e32 v134, 8, v9
	v_cndmask_b32_e64 v132, v134, v5, s[4:5]
	v_ashrrev_i32_e32 v133, 31, v132
	v_lshlrev_b64 v[132:133], 12, v[132:133]
	v_lshl_add_u64 v[132:133], v[0:1], 0, v[132:133]
	global_load_dwordx4 v[132:135], v[132:133], off nt
	v_add_u32_e32 v138, 12, v9
	v_cndmask_b32_e64 v136, v138, v6, s[4:5]
	v_ashrrev_i32_e32 v137, 31, v136
	v_lshlrev_b64 v[136:137], 12, v[136:137]
	v_lshl_add_u64 v[136:137], v[0:1], 0, v[136:137]
	global_load_dwordx4 v[136:139], v[136:137], off nt
	v_add_u32_e32 v142, 16, v9
	v_cndmask_b32_e64 v140, v142, v7, s[4:5]
	v_ashrrev_i32_e32 v141, 31, v140
	v_lshlrev_b64 v[140:141], 12, v[140:141]
	v_lshl_add_u64 v[140:141], v[0:1], 0, v[140:141]
	global_load_dwordx4 v[140:143], v[140:141], off nt
	s_max_i32 s36, s69, 1
	s_add_i32 s38, s36, -1
	s_and_b64 s[36:37], exec, s[4:5]
	s_cselect_b32 s70, 0, s38
	s_add_i32 s36, s69, 1
	s_min_i32 s38, s36, s72
	s_and_b64 s[36:37], exec, s[4:5]
	s_cselect_b32 s73, 0, s38
	s_mov_b32 s59, s99
	s_sub_i32 s72, s73, s70
	s_lshl_b64 s[36:37], s[58:59], 2
	s_add_u32 s36, s45, s36
	s_addc_u32 s37, s54, s37
	v_add_u32_e32 v0, s60, v169
	s_lshl_b32 s38, s70, 7
	v_ashrrev_i32_e32 v1, 31, v0
	s_add_i32 s38, s71, s38
	v_lshlrev_b64 v[0:1], 11, v[0:1]
	v_add_u32_e32 v4, s38, v169
	global_load_dword v16, v189, s[36:37]
	v_lshl_add_u64 v[0:1], s[50:51], 0, v[0:1]
	s_lshl_b32 s36, s3, 8
	s_mov_b32 s37, s99
	v_ashrrev_i32_e32 v5, 31, v4
	v_lshl_add_u64 v[0:1], v[0:1], 0, s[36:37]
	v_lshlrev_b64 v[4:5], 11, v[4:5]
	v_lshl_add_u64 v[0:1], v[0:1], 0, v[188:189]
	v_lshl_add_u64 v[4:5], s[50:51], 0, v[4:5]
	v_lshl_add_u64 v[4:5], v[4:5], 0, s[36:37]
	v_add_co_u32_e32 v18, vcc, s40, v0
	v_lshl_add_u64 v[38:39], v[4:5], 0, v[188:189]
	s_nop 0
	v_addc_co_u32_e32 v19, vcc, 0, v1, vcc
	global_load_dwordx4 v[4:7], v[0:1], off
	global_load_dwordx4 v[8:11], v[0:1], off offset:1024
	global_load_dwordx4 v[12:15], v[18:19], off
	s_nop 0
	global_load_dwordx4 v[18:21], v[18:19], off offset:1024
	v_add_co_u32_e32 v0, vcc, s40, v38
	s_mov_b32 s36, 0x20000
	s_nop 0
	v_addc_co_u32_e32 v1, vcc, 0, v39, vcc
	global_load_dwordx4 v[22:25], v[38:39], off
	global_load_dwordx4 v[26:29], v[38:39], off offset:1024
	global_load_dwordx4 v[30:33], v[0:1], off
	global_load_dwordx4 v[34:37], v[0:1], off offset:1024
	v_add_co_u32_e32 v0, vcc, s36, v38
	v_add_u32_e32 v17, 2, v3
	s_nop 0
	v_addc_co_u32_e32 v1, vcc, 0, v39, vcc
	v_add_co_u32_e32 v38, vcc, s41, v38
	v_add_u32_e32 v40, 8, v3
	s_nop 0
	v_addc_co_u32_e32 v39, vcc, 0, v39, vcc
	global_load_dwordx4 v[96:99], v[0:1], off
	global_load_dwordx4 v[100:103], v[0:1], off offset:1024
	global_load_dwordx4 v[104:107], v[38:39], off
	global_load_dwordx4 v[108:111], v[38:39], off offset:1024
	v_lshl_add_u32 v0, v2, 8, s63
	v_bitop3_b32 v1, v2, v3, 15 bitop3:0x6c
	v_add_u32_e32 v38, 4, v3
	v_add_u32_e32 v39, 6, v3
	v_add_u32_e32 v41, 10, v3
	v_add_u32_e32 v42, 12, v3
	v_add_u32_e32 v3, 14, v3
	v_lshl_add_u32 v1, v1, 4, v0
	v_bitop3_b32 v17, v17, v2, 15 bitop3:0x78
	v_bitop3_b32 v38, v38, v2, 15 bitop3:0x78
	v_bitop3_b32 v39, v39, v2, 15 bitop3:0x78
	v_bitop3_b32 v40, v40, v2, 15 bitop3:0x78
	v_bitop3_b32 v41, v41, v2, 15 bitop3:0x78
	v_bitop3_b32 v42, v42, v2, 15 bitop3:0x78
	v_bitop3_b32 v2, v3, v2, 15 bitop3:0x78
	v_lshl_add_u32 v3, v17, 4, v0
	v_lshl_add_u32 v17, v38, 4, v0
	v_lshl_add_u32 v38, v39, 4, v0
	v_lshl_add_u32 v39, v40, 4, v0
	v_lshl_add_u32 v40, v41, 4, v0
	v_lshl_add_u32 v41, v42, 4, v0
	v_lshl_add_u32 v0, v2, 4, v0
	s_waitcnt vmcnt(20)
	ds_write_b128 v60, v[112:115]
	s_waitcnt vmcnt(19)
	ds_write_b128 v61, v[116:119]
	s_waitcnt vmcnt(18)
	ds_write_b128 v62, v[120:123]
	s_waitcnt vmcnt(17)
	ds_write_b128 v63, v[124:127]
	s_waitcnt vmcnt(16)
	ds_write_b128 v60, v[128:131] offset:4096
	s_waitcnt vmcnt(15)
	ds_write_b128 v61, v[132:135] offset:4096
	s_waitcnt vmcnt(14)
	ds_write_b128 v62, v[136:139] offset:4096
	s_waitcnt vmcnt(13)
	ds_write_b128 v63, v[140:143] offset:4096
	ds_read_b128 v[112:115], v1
	ds_read_b128 v[116:119], v3
	ds_read_b128 v[120:123], v17
	ds_read_b128 v[124:127], v38
	ds_read_b128 v[128:131], v39
	ds_read_b128 v[132:135], v40
	ds_read_b128 v[136:139], v41
	ds_read_b128 v[140:143], v0
	s_cmp_gt_i32 s72, -2
	s_waitcnt lgkmcnt(0)
	s_barrier
; #define LAS __attribute__((address_space(3)))
; __device__ __forceinline__ void attn_phase(LAS unsigned char* lds, bf16_t* Qb, const bf16_t* KVb, const bf16_t* GZ, const float* sinkp) {
;     ...
;             *(LAS u32x4*)(Kt + soff) = k0r[0]; *(LAS u32x4*)(Kt + soff + 8192) = k0r[1]; *(LAS u32x4*)(Vt + soff) = v0r[0]; *(LAS u32x4*)(Vt + soff + 8192) = v0r[1];
;             *(LAS u32x4*)(Kt + 32768 + soff) = k1r[0]; *(LAS u32x4*)(Kt + 32768 + soff + 8192) = k1r[1]; *(LAS u32x4*)(Vt + 32768 + soff) = v1r[0]; *(LAS u32x4*)(Vt + 32768 + soff + 8192) = v1r[1];
;         }
;         for (int i = 0; i < ntiles; ++i) {
;             __syncthreads();
;             if (i >= 1 && i + 1 < ntiles) {
;                 const unsigned wb = ((i + 1) & 1) * 32768u;
;                 *(LAS u32x4*)(Kt + wb + soff) = kreg[0]; *(LAS u32x4*)(Kt + wb + soff + 8192) = kreg[1];
;                 *(LAS u32x4*)(Vt + wb + soff) = vreg[0]; *(LAS u32x4*)(Vt + wb + soff + 8192) = vreg[1];
;                 if (i + 2 < ntiles) {
;                     const int krow0 = sbase + (b0 + ((i + 1) >> 1)) * 128 + 64 * ((i + 1) & 1);
;                     const bf16_t* kp = KVb + (size_t)(krow0 + srow) * 1024 + kvh * 128 + sch * 8;
;                     kreg[0] = *(const u32x4*)kp; kreg[1] = *(const u32x4*)(kp + 32 * 1024); vreg[0] = *(const u32x4*)(kp + 512); vreg[1] = *(const u32x4*)(kp + 512 + 32 * 1024);
;                 }
;             }
;             const unsigned rb_off = (i & 1) * 32768u;
;             LAS unsigned char* Kc = Kt + rb_off; LAS unsigned char* Vc = Vt + rb_off;
;             if (i == 0) {
;                 f32x16 s0;
; #pragma unroll
;                 for (int r = 0; r < 16; ++r) s0[r] = 0.f;
; #pragma unroll
;                 for (int ks = 0; ks < 8; ++ks) {
;                     const bf16x8 k0 = *(const LAS bf16x8*)(Kc + kaddr[ks]);
;                     s0 = __builtin_amdgcn_mfma_f32_32x32x16_bf16(k0, qf[ks], s0, 0, 0, 0);
;                 }
;                 float mx = fmaxf(fmaxf(fmaxf(s0[0], s0[1]), fmaxf(s0[2], s0[3])), fmaxf(fmaxf(s0[4], s0[5]), fmaxf(s0[6], s0[7])));
;                 mx = fmaxf(mx, __shfl_xor(mx, 32));
;                 const float m_new = fmaxf(m_run, mx * SC), alpha = __builtin_amdgcn_exp2f(m_run - m_new);
;                 m_run = m_new;
;                 float rs = 0.f;
; #pragma unroll
	s_waitcnt vmcnt(11)
	ds_write_b128 v171, v[4:7]
	s_waitcnt vmcnt(10)
	ds_write_b128 v171, v[8:11] offset:16384
	s_waitcnt vmcnt(9)
	ds_write_b128 v171, v[12:15] offset:8192
	s_waitcnt vmcnt(8)
	ds_write_b128 v171, v[18:21] offset:24576
	s_waitcnt vmcnt(7)
	ds_write_b128 v171, v[22:25] offset:32768
	s_waitcnt vmcnt(5)
	ds_write_b128 v171, v[30:33] offset:40960
	ds_write_b128 v171, v[26:29] offset:49152
	s_waitcnt vmcnt(4)
	ds_write_b128 v171, v[34:37] offset:57344
	s_cbranch_scc0 .LBB0_181
	v_add_u32_e32 v0, 0, v150
	s_waitcnt lgkmcnt(0)
	s_barrier
	ds_read_b128 v[0:3], v0
	v_add_u32_e32 v4, 0, v151
	ds_read_b128 v[18:21], v4
	v_add_u32_e32 v17, 0, v152
	s_mov_b32 s36, 0x3fb8aa3b
	s_cmp_lt_i32 s72, 0
	s_waitcnt lgkmcnt(1)
	v_mfma_f32_32x32x16_bf16 v[0:15], v[0:3], v[112:115], 0
	s_waitcnt lgkmcnt(0)
	v_mfma_f32_32x32x16_bf16 v[0:15], v[18:21], v[116:119], v[0:15]
	ds_read_b128 v[18:21], v17
	v_add_u32_e32 v17, 0, v153
	ds_read_b128 v[22:25], v17
	v_add_u32_e32 v17, 0, v154
	s_waitcnt lgkmcnt(1)
	v_mfma_f32_32x32x16_bf16 v[0:15], v[18:21], v[120:123], v[0:15]
	ds_read_b128 v[18:21], v17
	v_add_u32_e32 v17, 0, v155
	s_waitcnt lgkmcnt(1)
	v_mfma_f32_32x32x16_bf16 v[0:15], v[22:25], v[124:127], v[0:15]
	ds_read_b128 v[22:25], v17
	v_add_u32_e32 v17, 0, v156
	s_waitcnt lgkmcnt(1)
	v_mfma_f32_32x32x16_bf16 v[0:15], v[18:21], v[128:131], v[0:15]
	ds_read_b128 v[18:21], v17
	v_add_u32_e32 v17, 0, v157
	s_waitcnt lgkmcnt(1)
	v_mfma_f32_32x32x16_bf16 v[0:15], v[22:25], v[132:135], v[0:15]
	ds_read_b128 v[22:25], v17
	v_xor_b32_e32 v17, 32, v232
	s_waitcnt lgkmcnt(1)
	v_mfma_f32_32x32x16_bf16 v[0:15], v[18:21], v[136:139], v[0:15]
	v_and_b32_e32 v18, 64, v232
	v_add_u32_e32 v18, 64, v18
	v_cmp_lt_i32_e32 vcc, v17, v18
	s_nop 1
	v_cndmask_b32_e32 v17, v232, v17, vcc
	v_lshlrev_b32_e32 v172, 2, v17
	s_waitcnt lgkmcnt(0)
	v_mfma_f32_32x32x16_bf16 v[0:15], v[22:25], v[140:143], v[0:15]
	s_nop 11
	v_max_f32_e32 v8, v1, v1
	v_max_f32_e32 v9, v0, v0
	v_max_f32_e32 v10, v3, v3
	v_max_f32_e32 v11, v2, v2
	v_max_f32_e32 v12, v7, v7
	v_max_f32_e32 v13, v6, v6
	v_max_f32_e32 v8, v9, v8
	v_max_f32_e32 v9, v11, v10
	v_max_f32_e32 v10, v13, v12
	v_max3_f32 v10, v4, v5, v10
	v_max3_f32 v8, v8, v9, v10
	ds_bpermute_b32 v9, v172, v8
	v_mul_f32_e32 v10, 0x3fb8aa3b, v16
	v_add_u32_e32 v11, 0, v161
	v_add_u32_e32 v12, 0, v162
	s_waitcnt lgkmcnt(0)
	v_max_f32_e32 v9, v9, v9
	v_max_f32_e32 v8, v8, v9
	v_mul_f32_e32 v8, 0x3e0293ee, v8
	v_max_f32_e32 v176, v10, v8
	v_fma_f32 v0, v0, s82, -v176
	v_fma_f32 v1, v1, s82, -v176
	v_fma_f32 v2, v2, s82, -v176
	v_fma_f32 v3, v3, s82, -v176
	v_fma_f32 v4, v4, s82, -v176
	v_fma_f32 v5, v5, s82, -v176
	v_fma_f32 v6, v6, s82, -v176
	v_fma_f32 v7, v7, s82, -v176
	v_exp_f32_e32 v13, v0
	v_exp_f32_e32 v14, v1
	v_exp_f32_e32 v15, v2
	v_exp_f32_e32 v65, v3
	v_exp_f32_e32 v66, v4
	v_exp_f32_e32 v67, v5
	v_exp_f32_e32 v68, v6
	v_exp_f32_e32 v69, v7
	v_cvt_pk_bf16_f32 v0, v13, v14
	v_cvt_pk_bf16_f32 v1, v15, v65
	v_cvt_pk_bf16_f32 v2, v66, v67
	v_cvt_pk_bf16_f32 v3, v68, v69
	ds_read_b64_tr_b16 v[4:5], v11 offset:16384
	ds_read_b64_tr_b16 v[6:7], v12 offset:16384
	v_add_u32_e32 v8, 0, v163
	v_add_u32_e32 v10, 0, v164
	ds_read_b64_tr_b16 v[8:9], v8 offset:16384
	ds_read_b64_tr_b16 v[10:11], v10 offset:16384
	s_waitcnt lgkmcnt(2)
	v_mfma_f32_32x32x16_bf16 v[48:63], v[4:7], v[0:3], 0
	v_add_u32_e32 v4, 0, v165
	v_add_u32_e32 v6, 0, v166
	ds_read_b64_tr_b16 v[4:5], v4 offset:16384
	ds_read_b64_tr_b16 v[6:7], v6 offset:16384
	v_add_u32_e32 v12, 0, v167
	v_add_f32_e32 v13, 0, v13
	s_waitcnt lgkmcnt(2)
	v_mfma_f32_32x32x16_bf16 v[32:47], v[8:11], v[0:3], 0
	v_add_u32_e32 v10, 0, v168
	v_fma_f32 v8, v16, s36, -v176
	v_exp_f32_e32 v70, v8
	ds_read_b64_tr_b16 v[8:9], v12 offset:16384
	ds_read_b64_tr_b16 v[10:11], v10 offset:16384
	v_add_f32_e32 v12, v14, v13
	s_waitcnt lgkmcnt(2)
	v_mfma_f32_32x32x16_bf16 v[16:31], v[4:7], v[0:3], 0
	v_add_f32_e32 v4, v15, v12
	v_add_f32_e32 v4, v65, v4
	v_add_f32_e32 v4, v66, v4
	v_add_f32_e32 v4, v67, v4
	v_add_f32_e32 v4, v68, v4
	v_add_f32_e32 v65, v69, v4
	ds_bpermute_b32 v66, v172, v65
	s_waitcnt lgkmcnt(1)
	v_mfma_f32_32x32x16_bf16 v[0:15], v[8:11], v[0:3], 0
	s_waitcnt lgkmcnt(0)
	v_add_f32_e32 v65, v65, v66
	v_add_f32_e32 v173, v70, v65
	s_cbranch_scc1 .LBB0_183
	s_lshl_b32 s3, s3, 7
	s_lshl_b32 s36, s3, 1
	s_mov_b32 s37, s99
	v_lshl_add_u64 v[146:147], v[144:145], 0, s[36:37]
	s_lshl_b32 s3, s73, 1
	s_lshl_b32 s36, s70, 1
	v_add_u32_e32 v174, s71, v169
	s_lshl_b32 s71, s72, 1
	s_sub_i32 s73, s3, s36
	s_add_i32 s72, s71, 3
	v_add_u32_e32 v175, 0x70, v64
	s_add_i32 s73, s73, 2
	s_mov_b32 s3, 0
	s_mov_b32 s75, 0x8000

; __device__ __forceinline__ unsigned cvt_pk_bf16(float lo, float hi) { unsigned r; asm volatile("v_cvt_pk_bf16_f32 %0, %1, %2" : "=v"(r) : "v"(lo), "v"(hi)); return r; }
; #define LAS __attribute__((address_space(3)))
; __device__ __forceinline__ void attn_phase(LAS unsigned char* lds, bf16_t* Qb, const bf16_t* KVb, const bf16_t* GZ, const float* sinkp) {
;     ...
;         const float inv = 1.f / l_run;
;         int qo = q, ho = h, cro = crr, cho = cch; asm volatile("" : "+v"(qo), "+v"(ho), "+v"(cro), "+v"(cho));
; #pragma unroll
;         for (int dt = 0; dt < 4; ++dt)
; #pragma unroll
;             for (int g4 = 0; g4 < 4; ++g4) {
;                 u32x2 ov; ov.x = cvt_pk_bf16(o[dt][4 * g4] * inv, o[dt][4 * g4 + 1] * inv); ov.y = cvt_pk_bf16(o[dt][4 * g4 + 2] * inv, o[dt][4 * g4 + 3] * inv);
;                 *(LAS u32x2*)(Wl + qo * 256 + (((4 * dt + g4) ^ (qo & 15)) << 4) + 8 * ho) = ov;
;             }
.LBB0_183:
	v_div_scale_f32 v64, s[6:7], v173, v173, 1.0
	v_rcp_f32_e32 v65, v64
	v_div_scale_f32 v66, vcc, 1.0, v173, 1.0
	s_movk_i32 s3, 0x50
	v_fma_f32 v67, -v64, v65, 1.0
	v_fmac_f32_e32 v65, v67, v65
	v_mul_f32_e32 v67, v66, v65
	v_fma_f32 v68, -v64, v67, v66
	v_fmac_f32_e32 v67, v68, v65
	v_fma_f32 v64, -v64, v67, v66
	v_div_fmas_f32 v64, v64, v65, v67
	v_div_fixup_f32 v66, v64, v173, 1.0
	v_mov_b32_e32 v67, v149
	v_mov_b32_e32 v64, v159
	v_mov_b32_e32 v68, v148
	v_mov_b32_e32 v65, v158
	v_mul_f32_e32 v48, v48, v66
	v_mul_f32_e32 v49, v49, v66
	v_cvt_pk_bf16_f32 v48, v48, v49
	v_mul_f32_e32 v49, v50, v66
	v_mul_f32_e32 v50, v51, v66
	v_lshlrev_b32_e32 v69, 8, v68
	v_lshlrev_b32_e32 v67, 3, v67
	v_cvt_pk_bf16_f32 v49, v49, v50
	v_lshlrev_b32_e32 v50, 4, v68
	v_add3_u32 v67, s63, v69, v67
	v_and_b32_e32 v50, 0xf0, v50
	v_add_u32_e32 v51, v67, v50
	ds_write_b64 v51, v[48:49]
	v_mul_f32_e32 v48, v52, v66
	v_mul_f32_e32 v49, v53, v66
	v_cvt_pk_bf16_f32 v48, v48, v49
	v_mul_f32_e32 v49, v54, v66
	v_mul_f32_e32 v51, v55, v66
	v_cvt_pk_bf16_f32 v49, v49, v51
	v_xad_u32 v51, v50, 16, v67
	ds_write_b64 v51, v[48:49]
	v_mul_f32_e32 v48, v56, v66
	v_mul_f32_e32 v49, v57, v66
	v_cvt_pk_bf16_f32 v48, v48, v49
	v_mul_f32_e32 v49, v58, v66
	v_mul_f32_e32 v51, v59, v66
	v_cvt_pk_bf16_f32 v49, v49, v51
	v_xad_u32 v51, v50, 32, v67
	ds_write_b64 v51, v[48:49]
	v_mul_f32_e32 v48, v60, v66
	v_mul_f32_e32 v49, v61, v66
	v_cvt_pk_bf16_f32 v48, v48, v49
	v_mul_f32_e32 v49, v62, v66
	v_mul_f32_e32 v51, v63, v66
	v_cvt_pk_bf16_f32 v49, v49, v51
	v_xad_u32 v51, v50, 48, v67
	v_mul_f32_e32 v32, v32, v66
	v_mul_f32_e32 v33, v33, v66
	ds_write_b64 v51, v[48:49]
	v_cvt_pk_bf16_f32 v32, v32, v33
	v_mul_f32_e32 v33, v34, v66
	v_mul_f32_e32 v34, v35, v66
	v_cvt_pk_bf16_f32 v33, v33, v34
	v_xad_u32 v34, v50, 64, v67
	ds_write_b64 v34, v[32:33]
	v_mul_f32_e32 v32, v36, v66
	v_mul_f32_e32 v33, v37, v66
	v_cvt_pk_bf16_f32 v32, v32, v33
	v_mul_f32_e32 v33, v38, v66
	v_mul_f32_e32 v34, v39, v66
	v_cvt_pk_bf16_f32 v33, v33, v34
	v_xad_u32 v34, v50, s3, v67
	ds_write_b64 v34, v[32:33]
	v_mul_f32_e32 v32, v40, v66
	v_mul_f32_e32 v33, v41, v66
	v_cvt_pk_bf16_f32 v32, v32, v33
	v_mul_f32_e32 v33, v42, v66
	v_mul_f32_e32 v34, v43, v66
	v_cvt_pk_bf16_f32 v33, v33, v34
	v_xad_u32 v34, v50, s43, v67
	ds_write_b64 v34, v[32:33]
	v_mul_f32_e32 v32, v44, v66
	v_mul_f32_e32 v33, v45, v66
	v_cvt_pk_bf16_f32 v32, v32, v33
	v_mul_f32_e32 v33, v46, v66
	v_mul_f32_e32 v34, v47, v66
	s_movk_i32 s3, 0x70
	v_cvt_pk_bf16_f32 v33, v33, v34
	v_xad_u32 v34, v50, s3, v67
	v_mul_f32_e32 v16, v16, v66
	v_mul_f32_e32 v17, v17, v66
	ds_write_b64 v34, v[32:33]
	v_cvt_pk_bf16_f32 v16, v16, v17
	v_mul_f32_e32 v17, v18, v66
	v_mul_f32_e32 v18, v19, v66
	s_movk_i32 s3, 0x80
	v_cvt_pk_bf16_f32 v17, v17, v18
	v_xad_u32 v18, v50, s3, v67
	ds_write_b64 v18, v[16:17]
	v_mul_f32_e32 v16, v20, v66
	v_mul_f32_e32 v17, v21, v66
	v_cvt_pk_bf16_f32 v16, v16, v17
	v_mul_f32_e32 v17, v22, v66
	v_mul_f32_e32 v18, v23, v66
	s_movk_i32 s3, 0x90
	v_cvt_pk_bf16_f32 v17, v17, v18
	v_xad_u32 v18, v50, s3, v67
	ds_write_b64 v18, v[16:17]
	v_mul_f32_e32 v16, v24, v66
	v_mul_f32_e32 v17, v25, v66
	v_cvt_pk_bf16_f32 v16, v16, v17
	v_mul_f32_e32 v17, v26, v66
	v_mul_f32_e32 v18, v27, v66
	s_movk_i32 s3, 0xa0
	v_cvt_pk_bf16_f32 v17, v17, v18
	v_xad_u32 v18, v50, s3, v67
	ds_write_b64 v18, v[16:17]
	v_mul_f32_e32 v16, v28, v66
	v_mul_f32_e32 v17, v29, v66
	v_cvt_pk_bf16_f32 v16, v16, v17
	v_mul_f32_e32 v17, v30, v66
	v_mul_f32_e32 v18, v31, v66
	s_movk_i32 s3, 0xb0
	v_cvt_pk_bf16_f32 v17, v17, v18
	v_xad_u32 v18, v50, s3, v67
	v_mul_f32_e32 v0, v0, v66
	v_mul_f32_e32 v1, v1, v66
	ds_write_b64 v18, v[16:17]
	v_cvt_pk_bf16_f32 v0, v0, v1
	v_mul_f32_e32 v1, v2, v66
	v_mul_f32_e32 v2, v3, v66
	s_movk_i32 s3, 0xc0
	v_cvt_pk_bf16_f32 v1, v1, v2
	v_xad_u32 v2, v50, s3, v67
	ds_write_b64 v2, v[0:1]
	v_mul_f32_e32 v0, v4, v66
	v_mul_f32_e32 v1, v5, v66
	v_cvt_pk_bf16_f32 v0, v0, v1
	v_mul_f32_e32 v1, v6, v66
	v_mul_f32_e32 v2, v7, v66
	s_movk_i32 s3, 0xd0
	v_cvt_pk_bf16_f32 v1, v1, v2
	v_xad_u32 v2, v50, s3, v67
	ds_write_b64 v2, v[0:1]
	v_mul_f32_e32 v0, v8, v66
	v_mul_f32_e32 v1, v9, v66
	v_cvt_pk_bf16_f32 v0, v0, v1
	v_mul_f32_e32 v1, v10, v66
	v_mul_f32_e32 v2, v11, v66
	s_movk_i32 s3, 0xe0
	v_cvt_pk_bf16_f32 v1, v1, v2
	v_xad_u32 v2, v50, s3, v67
	ds_write_b64 v2, v[0:1]
	v_mul_f32_e32 v0, v12, v66
	v_mul_f32_e32 v1, v13, v66
	v_cvt_pk_bf16_f32 v0, v0, v1
	v_mul_f32_e32 v1, v14, v66
	v_mul_f32_e32 v2, v15, v66
	s_movk_i32 s3, 0xf0
	v_cvt_pk_bf16_f32 v1, v1, v2
	v_xad_u32 v2, v50, s3, v67
	ds_write_b64 v2, v[0:1]
	v_lshlrev_b32_e32 v0, 3, v64
	v_readlane_b32 s70, v255, 3
	v_ashrrev_i32_e32 v1, 31, v0
	s_add_i32 s61, s61, s64
	v_readlane_b32 s71, v255, 4
	v_lshl_add_u64 v[4:5], v[0:1], 0, s[98:99]
	v_lshl_add_u32 v8, v65, 8, s68
	v_add_u32_e32 v9, s61, v65
	v_add_u32_e32 v8, 0xfffffc00, v8
	v_add_u32_e32 v10, 0, v65
	v_and_b32_e32 v0, 15, v10
; __device__ __forceinline__ unsigned cvt_pk_bf16(float lo, float hi) { unsigned r; asm volatile("v_cvt_pk_bf16_f32 %0, %1, %2" : "=v"(r) : "v"(lo), "v"(hi)); return r; }
; #define LAS __attribute__((address_space(3)))
; __device__ __forceinline__ void attn_phase(LAS unsigned char* lds, bf16_t* Qb, const bf16_t* KVb, const bf16_t* GZ, const float* sinkp) {
;     ...
; #pragma unroll 2
;         for (int it = 0; it < 8; ++it) {
;             const int rr = cro + 4 * it, grow = mu ? NREAL + seq * 16 + (rr & 15) : row0 + rr;
;             const u32x4 ovv = *(const LAS u32x4*)(Wl + rr * 256 + ((cho ^ (rr & 15)) << 4));
;             const size_t goff = (size_t)grow * 2048 + head * 128 + cho * 8;
;             const u32x4 gz = *(const u32x4*)(GZ + goff);
;             float fo[8], fg[8]; unpack8(ovv, fo); unpack8(gz, fg);
;             u32x4 res; res.x = cvt_pk_bf16(fo[0] * fg[0], fo[1] * fg[1]); res.y = cvt_pk_bf16(fo[2] * fg[2], fo[3] * fg[3]); res.z = cvt_pk_bf16(fo[4] * fg[4], fo[5] * fg[5]); res.w = cvt_pk_bf16(fo[6] * fg[6], fo[7] * fg[7]);
;             if (!mu || (w < 4 && rr < 16)) *(u32x4*)(Qb + goff) = res;
;         }
	v_or_b32_e32 v0, s60, v0
	v_add_u32_e32 v11, 0, v9
	v_cndmask_b32_e64 v0, v11, v0, s[4:5]
	v_ashrrev_i32_e32 v1, 31, v0
	v_lshlrev_b64 v[0:1], 11, v[0:1]
	v_lshl_add_u64 v[96:97], v[4:5], 0, v[0:1]
	v_lshl_add_u64 v[0:1], v[96:97], 1, s[48:49]
	global_load_dwordx4 v[24:27], v[0:1], off nt
	v_bitop3_b32 v12, v10, v64, 15 bitop3:0x6c
	v_lshl_add_u32 v12, v12, 4, v8
	ds_read_b128 v[112:115], v12
	v_add_u32_e32 v10, 4, v65
	v_and_b32_e32 v0, 15, v10
	v_or_b32_e32 v0, s60, v0
	v_add_u32_e32 v11, 4, v9
	v_cndmask_b32_e64 v0, v11, v0, s[4:5]
	v_ashrrev_i32_e32 v1, 31, v0
	v_lshlrev_b64 v[0:1], 11, v[0:1]
	v_lshl_add_u64 v[98:99], v[4:5], 0, v[0:1]
	v_lshl_add_u64 v[0:1], v[98:99], 1, s[48:49]
	global_load_dwordx4 v[28:31], v[0:1], off nt
	v_bitop3_b32 v12, v10, v64, 15 bitop3:0x6c
	v_lshl_add_u32 v12, v12, 4, v8
	ds_read_b128 v[116:119], v12 offset:1024
	v_add_u32_e32 v10, 8, v65
	v_and_b32_e32 v0, 15, v10
	v_or_b32_e32 v0, s60, v0
	v_add_u32_e32 v11, 8, v9
	v_cndmask_b32_e64 v0, v11, v0, s[4:5]
	v_ashrrev_i32_e32 v1, 31, v0
	v_lshlrev_b64 v[0:1], 11, v[0:1]
	v_lshl_add_u64 v[100:101], v[4:5], 0, v[0:1]
	v_lshl_add_u64 v[0:1], v[100:101], 1, s[48:49]
	global_load_dwordx4 v[32:35], v[0:1], off nt
	v_bitop3_b32 v12, v10, v64, 15 bitop3:0x6c
	v_lshl_add_u32 v12, v12, 4, v8
	ds_read_b128 v[120:123], v12 offset:2048
	v_add_u32_e32 v10, 12, v65
	v_and_b32_e32 v0, 15, v10
	v_or_b32_e32 v0, s60, v0
	v_add_u32_e32 v11, 12, v9
	v_cndmask_b32_e64 v0, v11, v0, s[4:5]
	v_ashrrev_i32_e32 v1, 31, v0
	v_lshlrev_b64 v[0:1], 11, v[0:1]
	v_lshl_add_u64 v[102:103], v[4:5], 0, v[0:1]
	v_lshl_add_u64 v[0:1], v[102:103], 1, s[48:49]
	global_load_dwordx4 v[36:39], v[0:1], off nt
	v_bitop3_b32 v12, v10, v64, 15 bitop3:0x6c
	v_lshl_add_u32 v12, v12, 4, v8
	ds_read_b128 v[124:127], v12 offset:3072
	v_add_u32_e32 v10, 16, v65
	v_and_b32_e32 v0, 15, v10
	v_or_b32_e32 v0, s60, v0
	v_add_u32_e32 v11, 16, v9
	v_cndmask_b32_e64 v0, v11, v0, s[4:5]
	v_ashrrev_i32_e32 v1, 31, v0
	v_lshlrev_b64 v[0:1], 11, v[0:1]
	v_lshl_add_u64 v[104:105], v[4:5], 0, v[0:1]
	v_lshl_add_u64 v[0:1], v[104:105], 1, s[48:49]
	global_load_dwordx4 v[40:43], v[0:1], off nt
	v_bitop3_b32 v12, v10, v64, 15 bitop3:0x6c
	v_lshl_add_u32 v12, v12, 4, v8
	ds_read_b128 v[128:131], v12 offset:4096
	v_add_u32_e32 v10, 20, v65
	v_and_b32_e32 v0, 15, v10
	v_or_b32_e32 v0, s60, v0
	v_add_u32_e32 v11, 20, v9
	v_cndmask_b32_e64 v0, v11, v0, s[4:5]
	v_ashrrev_i32_e32 v1, 31, v0
	v_lshlrev_b64 v[0:1], 11, v[0:1]
	v_lshl_add_u64 v[106:107], v[4:5], 0, v[0:1]
	v_lshl_add_u64 v[0:1], v[106:107], 1, s[48:49]
	global_load_dwordx4 v[44:47], v[0:1], off nt
	v_bitop3_b32 v12, v10, v64, 15 bitop3:0x6c
	v_lshl_add_u32 v12, v12, 4, v8
	ds_read_b128 v[132:135], v12 offset:5120
	v_add_u32_e32 v10, 24, v65
	v_and_b32_e32 v0, 15, v10
	v_or_b32_e32 v0, s60, v0
	v_add_u32_e32 v11, 24, v9
	v_cndmask_b32_e64 v0, v11, v0, s[4:5]
	v_ashrrev_i32_e32 v1, 31, v0
	v_lshlrev_b64 v[0:1], 11, v[0:1]
	v_lshl_add_u64 v[108:109], v[4:5], 0, v[0:1]
	v_lshl_add_u64 v[0:1], v[108:109], 1, s[48:49]
	global_load_dwordx4 v[48:51], v[0:1], off nt
	v_bitop3_b32 v12, v10, v64, 15 bitop3:0x6c
	v_lshl_add_u32 v12, v12, 4, v8
	ds_read_b128 v[136:139], v12 offset:6144
	v_add_u32_e32 v10, 28, v65
	v_and_b32_e32 v0, 15, v10
	v_or_b32_e32 v0, s60, v0
	v_add_u32_e32 v11, 28, v9
	v_cndmask_b32_e64 v0, v11, v0, s[4:5]
	v_ashrrev_i32_e32 v1, 31, v0
	v_lshlrev_b64 v[0:1], 11, v[0:1]
	v_lshl_add_u64 v[110:111], v[4:5], 0, v[0:1]
	v_lshl_add_u64 v[0:1], v[110:111], 1, s[48:49]
	global_load_dwordx4 v[52:55], v[0:1], off nt
	v_bitop3_b32 v12, v10, v64, 15 bitop3:0x6c
	v_lshl_add_u32 v12, v12, 4, v8
	ds_read_b128 v[140:143], v12 offset:7168
	s_waitcnt lgkmcnt(7)
	v_lshlrev_b32_e32 v16, 16, v112
	v_and_b32_e32 v112, 0xffff0000, v112
	v_lshlrev_b32_e32 v17, 16, v113
	v_and_b32_e32 v113, 0xffff0000, v113
	v_lshlrev_b32_e32 v18, 16, v114
	v_and_b32_e32 v114, 0xffff0000, v114
	v_lshlrev_b32_e32 v19, 16, v115
	v_and_b32_e32 v115, 0xffff0000, v115
	s_waitcnt vmcnt(7)
	v_lshlrev_b32_e32 v20, 16, v24
	v_and_b32_e32 v24, 0xffff0000, v24
	v_lshlrev_b32_e32 v21, 16, v25
	v_and_b32_e32 v25, 0xffff0000, v25
	v_lshlrev_b32_e32 v22, 16, v26
	v_and_b32_e32 v26, 0xffff0000, v26
	v_lshlrev_b32_e32 v23, 16, v27
	v_and_b32_e32 v27, 0xffff0000, v27
	v_mul_f32_e32 v0, v112, v24
	v_mul_f32_e32 v1, v113, v25
	v_mul_f32_e32 v2, v114, v26
	v_mul_f32_e32 v3, v115, v27
	v_mul_f32_e32 v16, v16, v20
	v_mul_f32_e32 v17, v17, v21
	v_mul_f32_e32 v18, v18, v22
	v_mul_f32_e32 v19, v19, v23
	v_cvt_pk_bf16_f32 v0, v16, v0
	v_cvt_pk_bf16_f32 v1, v17, v1
	v_cvt_pk_bf16_f32 v2, v18, v2
	v_cvt_pk_bf16_f32 v3, v19, v3
	v_add_u32_e32 v10, 0, v65
	v_cmp_lt_i32_e32 vcc, 15, v10
	s_or_b64 s[6:7], s[56:57], vcc
	s_and_b64 s[6:7], s[4:5], s[6:7]
	s_xor_b64 s[36:37], s[6:7], -1
	s_and_saveexec_b64 s[6:7], s[36:37]
	s_cbranch_execz .Lattn_ep_skip0
	v_lshl_add_u64 v[6:7], v[96:97], 1, s[16:17]
	global_store_dwordx4 v[6:7], v[0:3], off
